# layer1: 304 of the 528 PLE-projection GEMM units moved into gate-up's partial last round on idle CUs (rest stays beside the split down-proj tail)
# speedup vs baseline: 1.0058x; 1.0018x over previous
; #define GRID_BAR(k) grid_bar(bar, (unsigned)((k) + 1), (unsigned)G, (unsigned)bid, wave == 0 && lane_id() == 0)
; template <int l>
; __device__ __forceinline__ void run_layer(LAS unsigned char* lds, unsigned char* ws_in, float* out_in, const float* x_p, const float* x_s, const PIn* pin, const int G, const int bid, const int wave) {
;     ...
;         GRID_BAR(6 * l + 3);
;         {
;             pg8::RowOrder<2 * FF / 256> S; S.init(G, bid);
;             EpiGU E{ws, out, (1 + 2 * l) * MT};
;             pg8::gemm_phase<DM, EpiGU, pg8::RowOrder<2 * FF / 256>>(lds, HB, (const bf16*)(wb + W_GU), S, E, wave);
.Lp3b_after:
	s_mov_b32 s88, 0
	s_and_b64 vcc, exec, s[74:75]
	s_mov_b32 s0, s86
	s_cbranch_vccz .LBB0_1231
	s_and_b64 vcc, exec, s[74:75]
	s_mov_b32 s1, s0
	s_cbranch_vccz .LBB0_1232

; __device__ __forceinline__ int lane_id() { int l = __builtin_amdgcn_mbcnt_hi(~0u, __builtin_amdgcn_mbcnt_lo(~0u, 0u)); asm volatile("" : "+v"(l)); return l; }
; #define GRID_BAR(k) grid_bar(bar, (unsigned)((k) + 1), (unsigned)G, (unsigned)bid, wave == 0 && lane_id() == 0)
; template <int l>
; __device__ __forceinline__ void run_layer(LAS unsigned char* lds, unsigned char* ws_in, float* out_in, const float* x_p, const float* x_s, const PIn* pin, const int G, const int bid, const int wave) {
;     ...
;             pg8::gemm_phase<DM, EpiGU, pg8::RowOrder<2 * FF / 256>>(lds, HB, (const bf16*)(wb + W_GU), S, E, wave);
;             if (l == 0) {
;                 const int nbusy = (MT / 256 * (2 * FF / 256)) % G;
;                 if (S.vp >= nbusy) { const int lane = lane_id(); const PIn I = *pin;
;                     conv_p_caches(ws, out, I, 1, (size_t)(S.vp - nbusy) * (NWAVES * 64) + wave * 64 + lane, (size_t)(G - nbusy) * (NWAVES * 64), 1); }
;             }
;         }
;         GRID_BAR(6 * l + 4);
;         {
;             pg8::RowOrder<DM / 256> S; S.init(G, bid);
;             EpiRes E{ws, out, nullptr, nullptr, 0, -1};
;             pg8::gemm_phase<FF, EpiRes, pg8::RowOrder<DM / 256>>(lds, ACT, (const bf16*)(wb + W_D), S, E, wave);
;             pg8::RowOrderSkip<DM / 256> S2; S2.init(G, bid, (G > 16) ? (MT / 256 * 4) % G : 0);
;             EpiPP E2{ws, out};
;             pg8::gemm_phase<DPLE, EpiPP, pg8::RowOrderSkip<DM / 256>>(lds, (const bf16*)(ws + WS_PB) + (size_t)l * MT * DPLE, (const bf16*)(wb + W_PP), S2, E2, wave);
.LBB0_1253:
	s_cmp_lg_u32 s64, 0x100
	s_cbranch_scc1 .Lpp1b_nocall
	s_cmp_lg_u32 s88, 0
	s_cbranch_scc1 .Lpp1b_nocall
	s_mov_b32 s88, 1
	s_mov_b32 s89, s5
	s_mov_b32 s90, s29
	s_branch .LBB0_1301
.Lpp1b_ret:
	s_mov_b32 s5, s89
	s_mov_b32 s29, s90

; template <int l>
; __device__ __forceinline__ void run_layer(LAS unsigned char* lds, unsigned char* ws_in, float* out_in, const float* x_p, const float* x_s, const PIn* pin, const int G, const int bid, const int wave) {
;     ...
;             pg8::RowOrderSkip<DM / 256> S2; S2.init(G, bid, (G > 16) ? (MT / 256 * 4) % G : 0);
;             EpiPP E2{ws, out};
;             pg8::gemm_phase<DPLE, EpiPP, pg8::RowOrderSkip<DM / 256>>(lds, (const bf16*)(ws + WS_PB) + (size_t)l * MT * DPLE, (const bf16*)(wb + W_PP), S2, E2, wave);
.LBB0_1304:
	s_movk_i32 s91, 0x7fff
	s_cmp_lg_u32 s64, 0x100
	s_cbranch_scc1 .Lpp1b_m0
	s_cmp_eq_u32 s88, 1
	s_cbranch_scc1 .Lpp1b_m1
	s_mov_b32 s12, 64
	s_cmp_lg_u32 s88, 2
	s_cbranch_scc1 .Lpp1b_m0
	s_mov_b32 s91, 2
	s_cmp_lt_i32 s0, 64
	s_cbranch_scc1 .Lpp1b_m0
	s_addk_i32 s0, 0x130
	s_branch .Lpp1b_m0
.Lpp1b_m1:
	s_cmp_gt_i32 s0, 239
	s_cbranch_scc1 .LBB0_1331
	s_movk_i32 s12, 88
	s_mov_b32 s91, 2

; #define LAS __attribute__((address_space(3)))
; __device__ __forceinline__ int lane_id() { int l = __builtin_amdgcn_mbcnt_hi(~0u, __builtin_amdgcn_mbcnt_lo(~0u, 0u)); asm volatile("" : "+v"(l)); return l; }
; template <int KK, class Epi, class Sched, bool ALIGN_EPI = true>
; __device__ __forceinline__ void gemm_phase(LAS unsigned char* lds, const bf16* gA, const bf16* gBt, const Sched& S, const Epi& E, const int wid) {
;     const int lane = lane_id();
;     const int tid = wid * 64 + lane, wr = wid >> 2, wc = wid & 3, fr = lane & 15, fq = lane >> 4;
;     constexpr int K = KK, nt = K / BK;
;     unsigned voffA[2], voffB[2];
; #pragma unroll
;     for (int i = 0; i < 2; ++i) { int R, C; stage_rc(tid * 16 + i * 8192, R, C); const int Rb = Epi::PERM ? ((R & ~31) + perm32(R & 31)) : R;
;         voffA[i] = (unsigned)(R * K + C) * 2u; voffB[i] = (unsigned)(Rb * K + C) * 2u; }
;     const size_t kstep = (size_t)(BK * 2);
;     const size_t hstep = (size_t)HALF * K * 2;
;     const size_t tstep = 2 * hstep;
;     const unsigned ldsw = (unsigned)wid * 1024u;
;     const int aoff = lds_byte(wr * 64 + fr, fq * 8), boff = lds_byte(wc * 32 + fr, fq * 8);
.LBB0_1315:
	v_and_b32_e32 v1, 15, v0
	v_or_b32_e32 v2, s35, v1
	v_lshlrev_b32_e32 v4, 6, v2
	v_and_b32_e32 v5, 48, v0
	s_movk_i32 s10, 0x3c0
	v_ashrrev_i32_e32 v3, 6, v0
	v_and_or_b32 v4, v4, s10, v5
	v_readlane_b32 s10, v249, 43
	v_lshlrev_b32_e32 v0, 2, v0
	v_lshlrev_b32_e32 v2, 2, v2
	v_lshl_add_u32 v6, v3, 10, s10
	v_readlane_b32 s10, v249, 41
	v_lshl_or_b32 v1, v1, 6, v5
	v_add_lshl_u32 v3, v3, s94, 10
	v_and_b32_e32 v0, 32, v0
	s_cmpk_lt_u32 s10, 0x100
	v_and_b32_e32 v2, 32, v2
	v_bitop3_b32 v0, v1, v3, v0 bitop3:0xde
	s_waitcnt vmcnt(8)
	s_barrier
	s_waitcnt vmcnt(6)
	s_cselect_b64 s[10:11], -1, 0
	s_add_i32 s65, 0, 0x10000
	v_bitop3_b32 v2, v4, v6, v2 bitop3:0xde
	s_add_i32 s67, 0, 0x14000
	s_add_i32 s60, 0, 0x18000
	s_add_i32 s61, 0, 0x1c000
	v_add_u32_e32 v138, s65, v0
	s_add_i32 s65, s65, s33
	s_sub_i32 s59, s64, s12
	s_cmp_lg_u32 s88, 1
	s_cbranch_scc1 .Lpp1b_str
	s_movk_i32 s59, 0x98
.Lpp1b_str:
	v_add_u32_e32 v139, s67, v0
	v_add_u32_e32 v140, 0, v2
	v_add_u32_e32 v141, s60, v0
	v_add_u32_e32 v142, s61, v0
	s_add_i32 s62, s27, 0xc000
	s_add_i32 s63, s27, 0xe000
	s_add_i32 s66, s65, 0x2000
	s_add_i32 s67, s67, s33
	s_barrier
	s_branch .LBB0_1318

;     __device__ __forceinline__ bool next(int i, Unit& u) const {
;         if (v < nskip) return false;
;         const int L = i * (G - nskip) + (v - nskip); if (L >= (33792 / BM) * NN) return false;
;         constexpr int NM = 33792 / BM, NFULL = (NM / 8) * 8 * NN;
;         if (L < NFULL) { const int g = L / (8 * NN), idx = L % (8 * NN); u.pm = g * 8 + (idx & 7); u.pn = idx >> 3; }
;         else { constexpr int GS = NM % 8 ? NM % 8 : 8; const int idx = L - NFULL; u.pm = (NM / 8) * 8 + idx % GS; u.pn = idx / GS; }
;         return true;
.LBB0_1318:
	s_add_i32 s58, s58, 1
	s_mul_i32 s13, s58, s59
	s_add_i32 s13, s13, s0
	s_cmp_lt_u32 s58, s91
	s_cbranch_scc1 .Lpp1b_lim
	s_movk_i32 s13, 0x210
.Lpp1b_lim:
	s_cmpk_lt_i32 s13, 0x210
	s_cselect_b64 s[16:17], -1, 0
	s_cmpk_gt_i32 s13, 0x20f
	s_cbranch_scc1 .LBB0_1323
	s_cmpk_gt_i32 s13, 0x1ff
	s_mov_b64 s[18:19], -1
	s_cbranch_scc0 .LBB0_1321
	s_add_i32 s14, s13, 0xfffffe00
	s_and_b32 s12, s13, 3
	s_bitset1_b32 s12, 7
	s_lshr_b32 s14, s14, 2
	s_mov_b64 s[18:19], 0

; template <int l>
; __device__ __forceinline__ void run_layer(LAS unsigned char* lds, unsigned char* ws_in, float* out_in, const float* x_p, const float* x_s, const PIn* pin, const int G, const int bid, const int wave) {
;     ...
;             pg8::gemm_phase<DPLE, EpiPP, pg8::RowOrderSkip<DM / 256>>(lds, (const bf16*)(ws + WS_PB) + (size_t)l * MT * DPLE, (const bf16*)(wb + W_PP), S2, E2, wave);
.LBB0_1331:
	s_cmp_lg_u32 s88, 1
	s_cbranch_scc1 .Lpp1b_noret
	s_mov_b32 s88, 2
	s_branch .Lpp1b_ret
